# P8 gate/merge epilogues: counted vmcnt waits at first use of each loaded tile; consumers between cluster loads sunk behind the last load (on top of cmpkeep)
# speedup vs baseline: 1.0119x; 1.0063x over previous
.LBB0_670:
	s_lshl_b32 s22, s39, 8
	v_mbcnt_lo_u32_b32 v105, -1, 0
	v_mbcnt_hi_u32_b32 v105, -1, v105
	s_add_i32 s22, s22, s31
	v_and_or_b32 v104, v105, 15, s22
	s_lshl_b32 s22, s40, 8
	v_ashrrev_i32_e32 v105, 1, v105
	s_or_b32 s22, s22, s34
	v_and_b32_e32 v105, -8, v105
	v_add_u32_e32 v106, s22, v105
	v_mov_b64_e32 v[108:109], s[14:15]
	v_ashrrev_i32_e32 v107, 31, v106
	v_mad_i64_i32 v[108:109], s[22:23], v104, s72, v[108:109]
	v_lshlrev_b64 v[106:107], 1, v[106:107]
	v_lshl_add_u64 v[156:157], v[108:109], 0, v[106:107]
	global_load_dwordx4 v[162:165], v[156:157], off
	global_load_dwordx4 v[166:169], v[156:157], off offset:256
	v_ashrrev_i32_e32 v105, 31, v104
	v_lshlrev_b64 v[104:105], 11, v[104:105]
	v_lshl_add_u64 v[104:105], s[12:13], 0, v[104:105]
	v_lshl_add_u64 v[158:159], v[104:105], 0, v[106:107]
	v_add_co_u32_e32 v104, vcc, s51, v156
	s_mov_b32 s22, 0x48000
	s_nop 0
	v_addc_co_u32_e32 v105, vcc, 0, v157, vcc
	global_load_dwordx4 v[170:173], v[104:105], off
	global_load_dwordx4 v[120:123], v[104:105], off offset:256
	v_add_co_u32_e32 v104, vcc, s1, v156
	s_mov_b64 s[24:25], 0xc0000
	s_nop 0
	v_addc_co_u32_e32 v105, vcc, 0, v157, vcc
	global_load_dwordx4 v[116:119], v[104:105], off
	global_load_dwordx4 v[112:115], v[104:105], off offset:256
	v_add_co_u32_e32 v104, vcc, s22, v156
	v_mov_b64_e32 v[238:239], v[242:243]
	s_nop 0
	v_addc_co_u32_e32 v105, vcc, 0, v157, vcc
	global_load_dwordx4 v[108:111], v[104:105], off
	s_nop 0
	global_load_dwordx4 v[104:107], v[104:105], off offset:256
	v_mov_b64_e32 v[242:243], v[244:245]
	v_mov_b32_e32 v244, v251
	v_mov_b32_e32 v245, v240
	v_mov_b32_e32 v240, v246
	v_mov_b32_e32 v246, v247
	v_mov_b32_e32 v247, v248
	v_mov_b32_e32 v248, v249
	v_mov_b32_e32 v249, v250
	v_mov_b32_e32 v250, 0x4000
	v_mov_b32_e32 v251, 0x8000
	s_waitcnt lgkmcnt(0)
	s_waitcnt vmcnt(7)
	v_lshlrev_b32_e32 v174, 16, v162
	v_and_b32_e32 v175, 0xffff0000, v162
	v_lshlrev_b32_e32 v162, 16, v163
	v_and_b32_e32 v163, 0xffff0000, v163
	v_pk_fma_f32 v[148:149], v[148:149], v[162:163], 0 op_sel_hi:[1,1,0]
	v_lshlrev_b32_e32 v162, 16, v164
	v_and_b32_e32 v163, 0xffff0000, v164
	v_lshlrev_b32_e32 v164, 16, v165
	v_and_b32_e32 v165, 0xffff0000, v165
	v_pk_fma_f32 v[146:147], v[146:147], v[174:175], 0 op_sel_hi:[1,1,0]
	v_pk_fma_f32 v[164:165], v[144:145], v[164:165], 0 op_sel_hi:[1,1,0]
	v_pk_fma_f32 v[144:145], v[142:143], v[162:163], 0 op_sel_hi:[1,1,0]
	v_cvt_pk_bf16_f32 v142, v146, v147
	v_cvt_pk_bf16_f32 v143, v148, v149
	v_cvt_pk_bf16_f32 v144, v144, v145
	v_cvt_pk_bf16_f32 v145, v164, v165
	global_store_dwordx4 v[158:159], v[142:145], off
	s_nop 1
	s_waitcnt vmcnt(7)
	v_lshlrev_b32_e32 v142, 16, v166
	v_and_b32_e32 v143, 0xffff0000, v166
	v_lshlrev_b32_e32 v144, 16, v167
	v_and_b32_e32 v145, 0xffff0000, v167
	v_pk_fma_f32 v[140:141], v[140:141], v[144:145], 0 op_sel_hi:[1,1,0]
	v_pk_fma_f32 v[138:139], v[138:139], v[142:143], 0 op_sel_hi:[1,1,0]
	v_lshlrev_b32_e32 v142, 16, v168
	v_and_b32_e32 v143, 0xffff0000, v168
	v_lshlrev_b32_e32 v144, 16, v169
	v_and_b32_e32 v145, 0xffff0000, v169
	v_pk_fma_f32 v[144:145], v[134:135], v[144:145], 0 op_sel_hi:[1,1,0]
	v_pk_fma_f32 v[134:135], v[132:133], v[142:143], 0 op_sel_hi:[1,1,0]
	v_cvt_pk_bf16_f32 v132, v138, v139
	v_cvt_pk_bf16_f32 v133, v140, v141
	v_cvt_pk_bf16_f32 v134, v134, v135
	v_cvt_pk_bf16_f32 v135, v144, v145
	global_store_dwordx4 v[158:159], v[132:135], off offset:256
	s_nop 1
	s_waitcnt vmcnt(7)
	v_lshlrev_b32_e32 v132, 16, v170
	v_and_b32_e32 v133, 0xffff0000, v170
	v_lshlrev_b32_e32 v134, 16, v171
	v_and_b32_e32 v135, 0xffff0000, v171
	v_pk_fma_f32 v[130:131], v[130:131], v[134:135], 0 op_sel_hi:[1,1,0]
	v_pk_fma_f32 v[128:129], v[128:129], v[132:133], 0 op_sel_hi:[1,1,0]
	v_lshlrev_b32_e32 v132, 16, v172
	v_and_b32_e32 v133, 0xffff0000, v172
	v_lshlrev_b32_e32 v134, 16, v173
	v_and_b32_e32 v135, 0xffff0000, v173
	v_pk_fma_f32 v[134:135], v[126:127], v[134:135], 0 op_sel_hi:[1,1,0]
	v_pk_fma_f32 v[126:127], v[124:125], v[132:133], 0 op_sel_hi:[1,1,0]
	v_cvt_pk_bf16_f32 v124, v128, v129
	v_add_co_u32_e32 v128, vcc, s82, v158
	v_cvt_pk_bf16_f32 v125, v130, v131
	v_cvt_pk_bf16_f32 v126, v126, v127
	v_cvt_pk_bf16_f32 v127, v134, v135
	v_addc_co_u32_e32 v129, vcc, 0, v159, vcc
	global_store_dwordx4 v[128:129], v[124:127], off
	s_nop 1
	s_waitcnt vmcnt(7)
	v_lshlrev_b32_e32 v124, 16, v120
	v_and_b32_e32 v125, 0xffff0000, v120
	v_lshlrev_b32_e32 v120, 16, v121
	v_and_b32_e32 v121, 0xffff0000, v121
	v_pk_fma_f32 v[102:103], v[102:103], v[120:121], 0 op_sel_hi:[1,1,0]
	v_lshlrev_b32_e32 v120, 16, v122
	v_and_b32_e32 v121, 0xffff0000, v122
	v_lshlrev_b32_e32 v122, 16, v123
	v_and_b32_e32 v123, 0xffff0000, v123
	v_pk_fma_f32 v[100:101], v[100:101], v[124:125], 0 op_sel_hi:[1,1,0]
	v_pk_fma_f32 v[122:123], v[98:99], v[122:123], 0 op_sel_hi:[1,1,0]
	v_pk_fma_f32 v[98:99], v[96:97], v[120:121], 0 op_sel_hi:[1,1,0]
	v_cvt_pk_bf16_f32 v96, v100, v101
	v_cvt_pk_bf16_f32 v97, v102, v103
	v_cvt_pk_bf16_f32 v98, v98, v99
	v_cvt_pk_bf16_f32 v99, v122, v123
	global_store_dwordx4 v[128:129], v[96:99], off offset:256
	s_nop 1
	s_waitcnt vmcnt(7)
	v_lshlrev_b32_e32 v96, 16, v116
	v_and_b32_e32 v97, 0xffff0000, v116
	v_lshlrev_b32_e32 v98, 16, v117
	v_and_b32_e32 v99, 0xffff0000, v117
	v_pk_fma_f32 v[94:95], v[94:95], v[98:99], 0 op_sel_hi:[1,1,0]
	v_pk_fma_f32 v[92:93], v[92:93], v[96:97], 0 op_sel_hi:[1,1,0]
	v_lshlrev_b32_e32 v96, 16, v118
	v_and_b32_e32 v97, 0xffff0000, v118
	v_lshlrev_b32_e32 v98, 16, v119
	v_and_b32_e32 v99, 0xffff0000, v119
	v_pk_fma_f32 v[98:99], v[90:91], v[98:99], 0 op_sel_hi:[1,1,0]
	v_pk_fma_f32 v[90:91], v[88:89], v[96:97], 0 op_sel_hi:[1,1,0]
	v_cvt_pk_bf16_f32 v88, v92, v93
	v_add_co_u32_e32 v92, vcc, s94, v158
	v_cvt_pk_bf16_f32 v89, v94, v95
	v_cvt_pk_bf16_f32 v90, v90, v91
	v_cvt_pk_bf16_f32 v91, v98, v99
	v_addc_co_u32_e32 v93, vcc, 0, v159, vcc
	global_store_dwordx4 v[92:93], v[88:91], off
	s_nop 1
	s_waitcnt vmcnt(7)
	v_lshlrev_b32_e32 v88, 16, v112
	v_and_b32_e32 v89, 0xffff0000, v112
	v_lshlrev_b32_e32 v90, 16, v113
	v_and_b32_e32 v91, 0xffff0000, v113
	v_pk_fma_f32 v[86:87], v[86:87], v[90:91], 0 op_sel_hi:[1,1,0]
	v_pk_fma_f32 v[84:85], v[84:85], v[88:89], 0 op_sel_hi:[1,1,0]
	v_lshlrev_b32_e32 v88, 16, v114
	v_and_b32_e32 v89, 0xffff0000, v114
	v_lshlrev_b32_e32 v90, 16, v115
	v_and_b32_e32 v91, 0xffff0000, v115
	v_pk_fma_f32 v[90:91], v[82:83], v[90:91], 0 op_sel_hi:[1,1,0]
	v_pk_fma_f32 v[82:83], v[80:81], v[88:89], 0 op_sel_hi:[1,1,0]
	v_cvt_pk_bf16_f32 v80, v84, v85
	v_cvt_pk_bf16_f32 v81, v86, v87
	v_cvt_pk_bf16_f32 v82, v82, v83
	v_cvt_pk_bf16_f32 v83, v90, v91
	global_store_dwordx4 v[92:93], v[80:83], off offset:256
	s_nop 1
	s_waitcnt vmcnt(7)
	v_lshlrev_b32_e32 v80, 16, v108
	v_and_b32_e32 v81, 0xffff0000, v108
	v_lshlrev_b32_e32 v82, 16, v109
	v_and_b32_e32 v83, 0xffff0000, v109
	v_pk_fma_f32 v[78:79], v[78:79], v[82:83], 0 op_sel_hi:[1,1,0]
	v_pk_fma_f32 v[76:77], v[76:77], v[80:81], 0 op_sel_hi:[1,1,0]
	v_lshlrev_b32_e32 v80, 16, v110
	v_and_b32_e32 v81, 0xffff0000, v110
	v_lshlrev_b32_e32 v82, 16, v111
	v_and_b32_e32 v83, 0xffff0000, v111
	v_pk_fma_f32 v[82:83], v[74:75], v[82:83], 0 op_sel_hi:[1,1,0]
	v_pk_fma_f32 v[74:75], v[72:73], v[80:81], 0 op_sel_hi:[1,1,0]
	v_cvt_pk_bf16_f32 v72, v76, v77
	v_add_co_u32_e32 v76, vcc, s51, v158
	v_cvt_pk_bf16_f32 v73, v78, v79
	v_cvt_pk_bf16_f32 v74, v74, v75
	v_cvt_pk_bf16_f32 v75, v82, v83
	v_addc_co_u32_e32 v77, vcc, 0, v159, vcc
	global_store_dwordx4 v[76:77], v[72:75], off
	s_nop 1
	s_waitcnt vmcnt(7)
	v_lshlrev_b32_e32 v72, 16, v104
	v_and_b32_e32 v73, 0xffff0000, v104
	v_lshlrev_b32_e32 v74, 16, v105
	v_and_b32_e32 v75, 0xffff0000, v105
	v_pk_fma_f32 v[70:71], v[70:71], v[74:75], 0 op_sel_hi:[1,1,0]
	v_pk_fma_f32 v[68:69], v[68:69], v[72:73], 0 op_sel_hi:[1,1,0]
	v_lshlrev_b32_e32 v72, 16, v106
	v_and_b32_e32 v73, 0xffff0000, v106
	v_lshlrev_b32_e32 v74, 16, v107
	v_and_b32_e32 v75, 0xffff0000, v107
	v_pk_fma_f32 v[74:75], v[66:67], v[74:75], 0 op_sel_hi:[1,1,0]
	v_pk_fma_f32 v[66:67], v[64:65], v[72:73], 0 op_sel_hi:[1,1,0]
	v_cvt_pk_bf16_f32 v64, v68, v69
	v_cvt_pk_bf16_f32 v65, v70, v71
	v_cvt_pk_bf16_f32 v66, v66, v67
	v_cvt_pk_bf16_f32 v67, v74, v75
	v_lshl_add_u64 v[68:69], v[156:157], 0, s[24:25]
	v_lshl_add_u64 v[70:71], v[158:159], 0, s[78:79]
	global_store_dwordx4 v[76:77], v[64:67], off offset:256
	global_load_dwordx4 v[72:75], v[68:69], off
	global_load_dwordx4 v[76:79], v[68:69], off offset:256
	v_add_co_u32_e32 v64, vcc, s51, v68
	v_addc_co_u32_e32 v65, vcc, 0, v69, vcc
	global_load_dwordx4 v[80:83], v[64:65], off
	global_load_dwordx4 v[84:87], v[64:65], off offset:256
	v_add_co_u32_e32 v64, vcc, s1, v68
	s_nop 0
	v_addc_co_u32_e32 v65, vcc, 0, v69, vcc
	global_load_dwordx4 v[88:91], v[64:65], off
	global_load_dwordx4 v[92:95], v[64:65], off offset:256
	v_add_co_u32_e32 v64, vcc, s22, v68
	s_nop 0
	v_addc_co_u32_e32 v65, vcc, 0, v69, vcc
	global_load_dwordx4 v[96:99], v[64:65], off
	s_nop 0
	global_load_dwordx4 v[64:67], v[64:65], off offset:256
	s_waitcnt vmcnt(7)
	v_lshlrev_b32_e32 v100, 16, v72
	v_and_b32_e32 v101, 0xffff0000, v72
	v_lshlrev_b32_e32 v72, 16, v73
	v_and_b32_e32 v73, 0xffff0000, v73
	v_pk_fma_f32 v[62:63], v[62:63], v[72:73], 0 op_sel_hi:[1,1,0]
	v_lshlrev_b32_e32 v72, 16, v74
	v_and_b32_e32 v73, 0xffff0000, v74
	v_lshlrev_b32_e32 v74, 16, v75
	v_and_b32_e32 v75, 0xffff0000, v75
	v_pk_fma_f32 v[60:61], v[60:61], v[100:101], 0 op_sel_hi:[1,1,0]
	v_pk_fma_f32 v[74:75], v[58:59], v[74:75], 0 op_sel_hi:[1,1,0]
	v_pk_fma_f32 v[58:59], v[56:57], v[72:73], 0 op_sel_hi:[1,1,0]
	v_cvt_pk_bf16_f32 v56, v60, v61
	v_cvt_pk_bf16_f32 v57, v62, v63
	v_cvt_pk_bf16_f32 v58, v58, v59
	v_cvt_pk_bf16_f32 v59, v74, v75
	global_store_dwordx4 v[70:71], v[56:59], off
	s_mov_b64 s[22:23], -1
	s_nop 0
	s_waitcnt vmcnt(7)
	v_lshlrev_b32_e32 v56, 16, v76
	v_and_b32_e32 v57, 0xffff0000, v76
	v_lshlrev_b32_e32 v58, 16, v77
	v_and_b32_e32 v59, 0xffff0000, v77
	v_pk_fma_f32 v[54:55], v[54:55], v[58:59], 0 op_sel_hi:[1,1,0]
	v_pk_fma_f32 v[52:53], v[52:53], v[56:57], 0 op_sel_hi:[1,1,0]
	v_lshlrev_b32_e32 v56, 16, v78
	v_and_b32_e32 v57, 0xffff0000, v78
	v_lshlrev_b32_e32 v58, 16, v79
	v_and_b32_e32 v59, 0xffff0000, v79
	v_pk_fma_f32 v[58:59], v[50:51], v[58:59], 0 op_sel_hi:[1,1,0]
	v_pk_fma_f32 v[50:51], v[48:49], v[56:57], 0 op_sel_hi:[1,1,0]
	v_cvt_pk_bf16_f32 v48, v52, v53
	v_cvt_pk_bf16_f32 v49, v54, v55
	v_cvt_pk_bf16_f32 v50, v50, v51
	v_cvt_pk_bf16_f32 v51, v58, v59
	global_store_dwordx4 v[70:71], v[48:51], off offset:256
	s_waitcnt lgkmcnt(0)
	s_nop 0
	s_waitcnt vmcnt(7)
	v_lshlrev_b32_e32 v48, 16, v80
	v_and_b32_e32 v49, 0xffff0000, v80
	v_lshlrev_b32_e32 v50, 16, v81
	v_and_b32_e32 v51, 0xffff0000, v81
	v_pk_fma_f32 v[46:47], v[46:47], v[50:51], 0 op_sel_hi:[1,1,0]
	v_pk_fma_f32 v[44:45], v[44:45], v[48:49], 0 op_sel_hi:[1,1,0]
	v_lshlrev_b32_e32 v48, 16, v82
	v_and_b32_e32 v49, 0xffff0000, v82
	v_lshlrev_b32_e32 v50, 16, v83
	v_and_b32_e32 v51, 0xffff0000, v83
	v_pk_fma_f32 v[50:51], v[42:43], v[50:51], 0 op_sel_hi:[1,1,0]
	v_pk_fma_f32 v[42:43], v[40:41], v[48:49], 0 op_sel_hi:[1,1,0]
	v_cvt_pk_bf16_f32 v40, v44, v45
	v_add_co_u32_e32 v44, vcc, s82, v70
	v_cvt_pk_bf16_f32 v41, v46, v47
	v_cvt_pk_bf16_f32 v42, v42, v43
	v_cvt_pk_bf16_f32 v43, v50, v51
	v_addc_co_u32_e32 v45, vcc, 0, v71, vcc
	global_store_dwordx4 v[44:45], v[40:43], off
	s_nop 1
	s_waitcnt vmcnt(7)
	v_lshlrev_b32_e32 v40, 16, v84
	v_and_b32_e32 v41, 0xffff0000, v84
	v_lshlrev_b32_e32 v42, 16, v85
	v_and_b32_e32 v43, 0xffff0000, v85
	v_pk_fma_f32 v[38:39], v[38:39], v[42:43], 0 op_sel_hi:[1,1,0]
	v_pk_fma_f32 v[36:37], v[36:37], v[40:41], 0 op_sel_hi:[1,1,0]
	v_lshlrev_b32_e32 v40, 16, v86
	v_and_b32_e32 v41, 0xffff0000, v86
	v_lshlrev_b32_e32 v42, 16, v87
	v_and_b32_e32 v43, 0xffff0000, v87
	v_pk_fma_f32 v[42:43], v[34:35], v[42:43], 0 op_sel_hi:[1,1,0]
	v_pk_fma_f32 v[34:35], v[32:33], v[40:41], 0 op_sel_hi:[1,1,0]
	v_cvt_pk_bf16_f32 v32, v36, v37
	v_cvt_pk_bf16_f32 v33, v38, v39
	v_cvt_pk_bf16_f32 v34, v34, v35
	v_cvt_pk_bf16_f32 v35, v42, v43
	global_store_dwordx4 v[44:45], v[32:35], off offset:256
	s_nop 1
	s_waitcnt vmcnt(7)
	v_lshlrev_b32_e32 v32, 16, v88
	v_and_b32_e32 v33, 0xffff0000, v88
	v_lshlrev_b32_e32 v34, 16, v89
	v_and_b32_e32 v35, 0xffff0000, v89
	v_pk_fma_f32 v[30:31], v[30:31], v[34:35], 0 op_sel_hi:[1,1,0]
	v_pk_fma_f32 v[28:29], v[28:29], v[32:33], 0 op_sel_hi:[1,1,0]
	v_lshlrev_b32_e32 v32, 16, v90
	v_and_b32_e32 v33, 0xffff0000, v90
	v_lshlrev_b32_e32 v34, 16, v91
	v_and_b32_e32 v35, 0xffff0000, v91
	v_pk_fma_f32 v[34:35], v[26:27], v[34:35], 0 op_sel_hi:[1,1,0]
	v_pk_fma_f32 v[26:27], v[24:25], v[32:33], 0 op_sel_hi:[1,1,0]
	v_cvt_pk_bf16_f32 v24, v28, v29
	v_add_co_u32_e32 v28, vcc, s94, v70
	v_cvt_pk_bf16_f32 v25, v30, v31
	v_cvt_pk_bf16_f32 v26, v26, v27
	v_cvt_pk_bf16_f32 v27, v34, v35
	v_addc_co_u32_e32 v29, vcc, 0, v71, vcc
	global_store_dwordx4 v[28:29], v[24:27], off
	s_nop 1
	s_waitcnt vmcnt(7)
	v_lshlrev_b32_e32 v24, 16, v92
	v_and_b32_e32 v25, 0xffff0000, v92
	v_lshlrev_b32_e32 v26, 16, v93
	v_and_b32_e32 v27, 0xffff0000, v93
	v_pk_fma_f32 v[22:23], v[22:23], v[26:27], 0 op_sel_hi:[1,1,0]
	v_pk_fma_f32 v[20:21], v[20:21], v[24:25], 0 op_sel_hi:[1,1,0]
	v_lshlrev_b32_e32 v24, 16, v94
	v_and_b32_e32 v25, 0xffff0000, v94
	v_lshlrev_b32_e32 v26, 16, v95
	v_and_b32_e32 v27, 0xffff0000, v95
	v_pk_fma_f32 v[26:27], v[18:19], v[26:27], 0 op_sel_hi:[1,1,0]
	v_pk_fma_f32 v[18:19], v[16:17], v[24:25], 0 op_sel_hi:[1,1,0]
	v_cvt_pk_bf16_f32 v16, v20, v21
	v_cvt_pk_bf16_f32 v17, v22, v23
	v_cvt_pk_bf16_f32 v18, v18, v19
	v_cvt_pk_bf16_f32 v19, v26, v27
	global_store_dwordx4 v[28:29], v[16:19], off offset:256
	s_nop 1
	s_waitcnt vmcnt(7)
	v_lshlrev_b32_e32 v16, 16, v96
	v_and_b32_e32 v17, 0xffff0000, v96
	v_lshlrev_b32_e32 v18, 16, v97
	v_and_b32_e32 v19, 0xffff0000, v97
	v_pk_fma_f32 v[14:15], v[14:15], v[18:19], 0 op_sel_hi:[1,1,0]
	v_pk_fma_f32 v[12:13], v[12:13], v[16:17], 0 op_sel_hi:[1,1,0]
	v_lshlrev_b32_e32 v16, 16, v98
	v_and_b32_e32 v17, 0xffff0000, v98
	v_lshlrev_b32_e32 v18, 16, v99
	v_and_b32_e32 v19, 0xffff0000, v99
	v_pk_fma_f32 v[18:19], v[10:11], v[18:19], 0 op_sel_hi:[1,1,0]
	v_pk_fma_f32 v[10:11], v[8:9], v[16:17], 0 op_sel_hi:[1,1,0]
	v_cvt_pk_bf16_f32 v8, v12, v13
	v_add_co_u32_e32 v12, vcc, s51, v70
	v_cvt_pk_bf16_f32 v9, v14, v15
	v_cvt_pk_bf16_f32 v10, v10, v11
	v_cvt_pk_bf16_f32 v11, v18, v19
	v_addc_co_u32_e32 v13, vcc, 0, v71, vcc
	global_store_dwordx4 v[12:13], v[8:11], off
	s_and_b64 vcc, exec, s[2:3]
	s_nop 0
	s_waitcnt vmcnt(7)
	v_lshlrev_b32_e32 v8, 16, v64
	v_and_b32_e32 v9, 0xffff0000, v64
	v_lshlrev_b32_e32 v10, 16, v65
	v_and_b32_e32 v11, 0xffff0000, v65
	v_pk_fma_f32 v[6:7], v[6:7], v[10:11], 0 op_sel_hi:[1,1,0]
	v_pk_fma_f32 v[4:5], v[4:5], v[8:9], 0 op_sel_hi:[1,1,0]
	v_lshlrev_b32_e32 v8, 16, v66
	v_and_b32_e32 v9, 0xffff0000, v66
	v_lshlrev_b32_e32 v10, 16, v67
	v_and_b32_e32 v11, 0xffff0000, v67
	v_pk_fma_f32 v[10:11], v[2:3], v[10:11], 0 op_sel_hi:[1,1,0]
	v_pk_fma_f32 v[2:3], v[0:1], v[8:9], 0 op_sel_hi:[1,1,0]
	v_cvt_pk_bf16_f32 v0, v4, v5
	v_cvt_pk_bf16_f32 v1, v6, v7
	v_cvt_pk_bf16_f32 v2, v2, v3
	v_cvt_pk_bf16_f32 v3, v10, v11
	global_store_dwordx4 v[12:13], v[0:3], off offset:256
	s_nop 1
	v_lshl_add_u64 v[0:1], v[68:69], 0, s[24:25]
	v_lshl_add_u64 v[2:3], v[70:71], 0, s[78:79]
	s_cbranch_vccnz .LBB0_657
	s_andn2_b64 vcc, exec, s[10:11]
	s_cbranch_vccnz .LBB0_656
	s_barrier
	s_branch .LBB0_656

.LBB0_696:
	s_lshl_b32 s4, s45, 8
	v_mbcnt_lo_u32_b32 v129, -1, 0
	v_mbcnt_hi_u32_b32 v129, -1, v129
	s_add_i32 s4, s4, s39
	v_and_or_b32 v128, v129, 15, s4
	s_lshl_b32 s4, s52, 8
	v_ashrrev_i32_e32 v129, 1, v129
	s_or_b32 s4, s4, s40
	v_and_b32_e32 v129, -8, v129
	v_add_u32_e32 v130, s4, v129
	v_ashrrev_i32_e32 v129, 31, v128
	v_mov_b64_e32 v[132:133], s[14:15]
	v_ashrrev_i32_e32 v131, 31, v130
	v_mad_i64_i32 v[132:133], s[4:5], v128, s72, v[132:133]
	v_lshlrev_b64 v[130:131], 1, v[130:131]
	v_lshlrev_b64 v[128:129], 11, v[128:129]
	v_lshl_add_u64 v[196:197], v[132:133], 0, v[130:131]
	v_lshl_add_u64 v[128:129], s[12:13], 0, v[128:129]
	v_lshl_add_u64 v[198:199], v[128:129], 0, v[130:131]
	global_load_dwordx4 v[204:207], v[196:197], off
	global_load_dwordx4 v[220:223], v[198:199], off
	global_load_dwordx4 v[174:177], v[196:197], off offset:256
	global_load_dwordx4 v[182:185], v[198:199], off offset:256
	v_add_co_u32_e32 v128, vcc, s51, v196
	s_mov_b32 s4, 0x48000
	s_nop 0
	v_addc_co_u32_e32 v129, vcc, 0, v197, vcc
	global_load_dwordx4 v[170:173], v[128:129], off
	v_add_co_u32_e32 v218, vcc, s82, v198
	s_mov_b64 s[24:25], 0xc0000
	s_nop 0
	v_addc_co_u32_e32 v219, vcc, 0, v199, vcc
	global_load_dwordx4 v[178:181], v[218:219], off
	global_load_dwordx4 v[158:161], v[128:129], off offset:256
	global_load_dwordx4 v[166:169], v[218:219], off offset:256
	v_add_co_u32_e32 v128, vcc, s1, v196
	v_addc_co_u32_e32 v129, vcc, 0, v197, vcc
	global_load_dwordx4 v[154:157], v[128:129], off
	v_add_co_u32_e32 v216, vcc, s94, v198
	s_nop 0
	v_addc_co_u32_e32 v217, vcc, 0, v199, vcc
	global_load_dwordx4 v[162:165], v[216:217], off
	global_load_dwordx4 v[142:145], v[128:129], off offset:256
	global_load_dwordx4 v[150:153], v[216:217], off offset:256
	v_add_co_u32_e32 v128, vcc, s4, v196
	s_nop 0
	v_addc_co_u32_e32 v129, vcc, 0, v197, vcc
	global_load_dwordx4 v[132:135], v[128:129], off
	v_add_co_u32_e32 v200, vcc, s51, v198
	s_nop 0
	v_addc_co_u32_e32 v201, vcc, 0, v199, vcc
	global_load_dwordx4 v[146:149], v[200:201], off
	s_nop 0
	global_load_dwordx4 v[128:131], v[128:129], off offset:256
	s_nop 0
	global_load_dwordx4 v[138:141], v[200:201], off offset:256
	s_waitcnt vmcnt(14)
	v_lshlrev_b32_e32 v208, 16, v220
	v_and_b32_e32 v209, 0xffff0000, v220
	v_lshlrev_b32_e32 v210, 16, v221
	v_and_b32_e32 v211, 0xffff0000, v221
	v_lshlrev_b32_e32 v220, 16, v204
	v_and_b32_e32 v221, 0xffff0000, v204
	v_lshlrev_b32_e32 v204, 16, v205
	v_and_b32_e32 v205, 0xffff0000, v205
	v_lshlrev_b32_e32 v212, 16, v222
	v_and_b32_e32 v213, 0xffff0000, v222
	v_lshlrev_b32_e32 v214, 16, v223
	v_and_b32_e32 v215, 0xffff0000, v223
	v_pk_fma_f32 v[126:127], v[126:127], v[204:205], v[210:211]
	v_lshlrev_b32_e32 v204, 16, v206
	v_and_b32_e32 v205, 0xffff0000, v206
	v_lshlrev_b32_e32 v206, 16, v207
	v_and_b32_e32 v207, 0xffff0000, v207
	v_pk_fma_f32 v[124:125], v[124:125], v[220:221], v[208:209]
	v_pk_fma_f32 v[206:207], v[122:123], v[206:207], v[214:215]
	v_pk_fma_f32 v[122:123], v[120:121], v[204:205], v[212:213]
	v_cvt_pk_bf16_f32 v120, v124, v125
	v_cvt_pk_bf16_f32 v121, v126, v127
	v_cvt_pk_bf16_f32 v122, v122, v123
	v_cvt_pk_bf16_f32 v123, v206, v207
	global_store_dwordx4 v[198:199], v[120:123], off
	s_waitcnt vmcnt(13)
	v_lshlrev_b32_e32 v124, 16, v184
	v_and_b32_e32 v125, 0xffff0000, v184
	v_lshlrev_b32_e32 v120, 16, v182
	v_and_b32_e32 v121, 0xffff0000, v182
	v_lshlrev_b32_e32 v122, 16, v183
	v_and_b32_e32 v123, 0xffff0000, v183
	v_lshlrev_b32_e32 v182, 16, v174
	v_and_b32_e32 v183, 0xffff0000, v174
	v_lshlrev_b32_e32 v174, 16, v175
	v_and_b32_e32 v175, 0xffff0000, v175
	v_lshlrev_b32_e32 v126, 16, v185
	v_and_b32_e32 v127, 0xffff0000, v185
	v_pk_fma_f32 v[118:119], v[118:119], v[174:175], v[122:123]
	v_pk_fma_f32 v[116:117], v[116:117], v[182:183], v[120:121]
	v_lshlrev_b32_e32 v120, 16, v176
	v_and_b32_e32 v121, 0xffff0000, v176
	v_lshlrev_b32_e32 v122, 16, v177
	v_and_b32_e32 v123, 0xffff0000, v177
	v_pk_fma_f32 v[122:123], v[114:115], v[122:123], v[126:127]
	v_pk_fma_f32 v[114:115], v[112:113], v[120:121], v[124:125]
	v_cvt_pk_bf16_f32 v112, v116, v117
	v_cvt_pk_bf16_f32 v113, v118, v119
	v_cvt_pk_bf16_f32 v114, v114, v115
	v_cvt_pk_bf16_f32 v115, v122, v123
	global_store_dwordx4 v[198:199], v[112:115], off offset:256
	s_waitcnt vmcnt(13)
	v_lshlrev_b32_e32 v120, 16, v170
	v_and_b32_e32 v121, 0xffff0000, v170
	s_waitcnt vmcnt(12)
	v_lshlrev_b32_e32 v112, 16, v178
	v_and_b32_e32 v113, 0xffff0000, v178
	v_lshlrev_b32_e32 v114, 16, v179
	v_and_b32_e32 v115, 0xffff0000, v179
	v_lshlrev_b32_e32 v122, 16, v171
	v_and_b32_e32 v123, 0xffff0000, v171
	v_lshlrev_b32_e32 v116, 16, v180
	v_and_b32_e32 v117, 0xffff0000, v180
	v_lshlrev_b32_e32 v118, 16, v181
	v_and_b32_e32 v119, 0xffff0000, v181
	v_pk_fma_f32 v[110:111], v[110:111], v[122:123], v[114:115]
	v_pk_fma_f32 v[108:109], v[108:109], v[120:121], v[112:113]
	v_lshlrev_b32_e32 v112, 16, v172
	v_and_b32_e32 v113, 0xffff0000, v172
	v_lshlrev_b32_e32 v114, 16, v173
	v_and_b32_e32 v115, 0xffff0000, v173
	v_pk_fma_f32 v[114:115], v[106:107], v[114:115], v[118:119]
	v_pk_fma_f32 v[106:107], v[104:105], v[112:113], v[116:117]
	v_cvt_pk_bf16_f32 v104, v108, v109
	v_cvt_pk_bf16_f32 v105, v110, v111
	v_cvt_pk_bf16_f32 v106, v106, v107
	v_cvt_pk_bf16_f32 v107, v114, v115
	global_store_dwordx4 v[218:219], v[104:107], off
	s_waitcnt vmcnt(12)
	v_lshlrev_b32_e32 v112, 16, v158
	v_and_b32_e32 v113, 0xffff0000, v158
	s_waitcnt vmcnt(11)
	v_lshlrev_b32_e32 v104, 16, v166
	v_and_b32_e32 v105, 0xffff0000, v166
	v_lshlrev_b32_e32 v106, 16, v167
	v_and_b32_e32 v107, 0xffff0000, v167
	v_lshlrev_b32_e32 v114, 16, v159
	v_and_b32_e32 v115, 0xffff0000, v159
	v_lshlrev_b32_e32 v108, 16, v168
	v_and_b32_e32 v109, 0xffff0000, v168
	v_lshlrev_b32_e32 v110, 16, v169
	v_and_b32_e32 v111, 0xffff0000, v169
	v_pk_fma_f32 v[102:103], v[102:103], v[114:115], v[106:107]
	v_pk_fma_f32 v[100:101], v[100:101], v[112:113], v[104:105]
	v_lshlrev_b32_e32 v104, 16, v160
	v_and_b32_e32 v105, 0xffff0000, v160
	v_lshlrev_b32_e32 v106, 16, v161
	v_and_b32_e32 v107, 0xffff0000, v161
	v_pk_fma_f32 v[106:107], v[98:99], v[106:107], v[110:111]
	v_pk_fma_f32 v[98:99], v[96:97], v[104:105], v[108:109]
	v_cvt_pk_bf16_f32 v96, v100, v101
	v_cvt_pk_bf16_f32 v97, v102, v103
	v_cvt_pk_bf16_f32 v98, v98, v99
	v_cvt_pk_bf16_f32 v99, v106, v107
	global_store_dwordx4 v[218:219], v[96:99], off offset:256
	s_waitcnt lgkmcnt(0)
	s_waitcnt vmcnt(11)
	v_lshlrev_b32_e32 v104, 16, v154
	v_and_b32_e32 v105, 0xffff0000, v154
	s_waitcnt vmcnt(10)
	v_lshlrev_b32_e32 v96, 16, v162
	v_and_b32_e32 v97, 0xffff0000, v162
	v_lshlrev_b32_e32 v98, 16, v163
	v_and_b32_e32 v99, 0xffff0000, v163
	v_lshlrev_b32_e32 v106, 16, v155
	v_and_b32_e32 v107, 0xffff0000, v155
	v_lshlrev_b32_e32 v100, 16, v164
	v_and_b32_e32 v101, 0xffff0000, v164
	v_lshlrev_b32_e32 v102, 16, v165
	v_and_b32_e32 v103, 0xffff0000, v165
	v_pk_fma_f32 v[94:95], v[94:95], v[106:107], v[98:99]
	v_pk_fma_f32 v[92:93], v[92:93], v[104:105], v[96:97]
	v_lshlrev_b32_e32 v96, 16, v156
	v_and_b32_e32 v97, 0xffff0000, v156
	v_lshlrev_b32_e32 v98, 16, v157
	v_and_b32_e32 v99, 0xffff0000, v157
	v_pk_fma_f32 v[98:99], v[90:91], v[98:99], v[102:103]
	v_pk_fma_f32 v[90:91], v[88:89], v[96:97], v[100:101]
	v_cvt_pk_bf16_f32 v88, v92, v93
	v_cvt_pk_bf16_f32 v89, v94, v95
	v_cvt_pk_bf16_f32 v90, v90, v91
	v_cvt_pk_bf16_f32 v91, v98, v99
	global_store_dwordx4 v[216:217], v[88:91], off
	s_waitcnt vmcnt(10)
	v_lshlrev_b32_e32 v96, 16, v142
	v_and_b32_e32 v97, 0xffff0000, v142
	s_waitcnt vmcnt(9)
	v_lshlrev_b32_e32 v88, 16, v150
	v_and_b32_e32 v89, 0xffff0000, v150
	v_lshlrev_b32_e32 v90, 16, v151
	v_and_b32_e32 v91, 0xffff0000, v151
	v_lshlrev_b32_e32 v98, 16, v143
	v_and_b32_e32 v99, 0xffff0000, v143
	v_lshlrev_b32_e32 v92, 16, v152
	v_and_b32_e32 v93, 0xffff0000, v152
	v_lshlrev_b32_e32 v94, 16, v153
	v_and_b32_e32 v95, 0xffff0000, v153
	v_pk_fma_f32 v[86:87], v[86:87], v[98:99], v[90:91]
	v_pk_fma_f32 v[84:85], v[84:85], v[96:97], v[88:89]
	v_lshlrev_b32_e32 v88, 16, v144
	v_and_b32_e32 v89, 0xffff0000, v144
	v_lshlrev_b32_e32 v90, 16, v145
	v_and_b32_e32 v91, 0xffff0000, v145
	v_pk_fma_f32 v[90:91], v[82:83], v[90:91], v[94:95]
	v_pk_fma_f32 v[82:83], v[80:81], v[88:89], v[92:93]
	v_cvt_pk_bf16_f32 v80, v84, v85
	v_cvt_pk_bf16_f32 v81, v86, v87
	v_cvt_pk_bf16_f32 v82, v82, v83
	v_cvt_pk_bf16_f32 v83, v90, v91
	global_store_dwordx4 v[216:217], v[80:83], off offset:256
	s_waitcnt vmcnt(9)
	v_lshlrev_b32_e32 v88, 16, v132
	v_and_b32_e32 v89, 0xffff0000, v132
	s_waitcnt vmcnt(8)
	v_lshlrev_b32_e32 v80, 16, v146
	v_and_b32_e32 v81, 0xffff0000, v146
	v_lshlrev_b32_e32 v82, 16, v147
	v_and_b32_e32 v83, 0xffff0000, v147
	v_lshlrev_b32_e32 v90, 16, v133
	v_and_b32_e32 v91, 0xffff0000, v133
	v_lshlrev_b32_e32 v84, 16, v148
	v_and_b32_e32 v85, 0xffff0000, v148
	v_lshlrev_b32_e32 v86, 16, v149
	v_and_b32_e32 v87, 0xffff0000, v149
	v_pk_fma_f32 v[78:79], v[78:79], v[90:91], v[82:83]
	v_pk_fma_f32 v[76:77], v[76:77], v[88:89], v[80:81]
	v_lshlrev_b32_e32 v80, 16, v134
	v_and_b32_e32 v81, 0xffff0000, v134
	v_lshlrev_b32_e32 v82, 16, v135
	v_and_b32_e32 v83, 0xffff0000, v135
	v_pk_fma_f32 v[82:83], v[74:75], v[82:83], v[86:87]
	v_pk_fma_f32 v[74:75], v[72:73], v[80:81], v[84:85]
	v_cvt_pk_bf16_f32 v72, v76, v77
	v_cvt_pk_bf16_f32 v73, v78, v79
	v_cvt_pk_bf16_f32 v74, v74, v75
	v_cvt_pk_bf16_f32 v75, v82, v83
	global_store_dwordx4 v[200:201], v[72:75], off
	s_waitcnt vmcnt(8)
	v_lshlrev_b32_e32 v80, 16, v128
	v_and_b32_e32 v81, 0xffff0000, v128
	s_waitcnt vmcnt(7)
	v_lshlrev_b32_e32 v72, 16, v138
	v_and_b32_e32 v73, 0xffff0000, v138
	v_lshlrev_b32_e32 v74, 16, v139
	v_and_b32_e32 v75, 0xffff0000, v139
	v_lshlrev_b32_e32 v82, 16, v129
	v_and_b32_e32 v83, 0xffff0000, v129
	v_lshlrev_b32_e32 v76, 16, v140
	v_and_b32_e32 v77, 0xffff0000, v140
	v_lshlrev_b32_e32 v78, 16, v141
	v_and_b32_e32 v79, 0xffff0000, v141
	v_pk_fma_f32 v[70:71], v[70:71], v[82:83], v[74:75]
	v_pk_fma_f32 v[68:69], v[68:69], v[80:81], v[72:73]
	v_lshlrev_b32_e32 v72, 16, v130
	v_and_b32_e32 v73, 0xffff0000, v130
	v_lshlrev_b32_e32 v74, 16, v131
	v_and_b32_e32 v75, 0xffff0000, v131
	v_pk_fma_f32 v[74:75], v[66:67], v[74:75], v[78:79]
	v_pk_fma_f32 v[66:67], v[64:65], v[72:73], v[76:77]
	v_cvt_pk_bf16_f32 v64, v68, v69
	v_cvt_pk_bf16_f32 v65, v70, v71
	v_cvt_pk_bf16_f32 v66, v66, v67
	v_cvt_pk_bf16_f32 v67, v74, v75
	v_lshl_add_u64 v[92:93], v[196:197], 0, s[24:25]
	v_lshl_add_u64 v[94:95], v[198:199], 0, s[78:79]
	global_store_dwordx4 v[200:201], v[64:67], off offset:256
	global_load_dwordx4 v[102:105], v[92:93], off
	global_load_dwordx4 v[106:109], v[94:95], off
	global_load_dwordx4 v[110:113], v[92:93], off offset:256
	global_load_dwordx4 v[114:117], v[94:95], off offset:256
	v_add_co_u32_e32 v64, vcc, s51, v92
	v_addc_co_u32_e32 v65, vcc, 0, v93, vcc
	global_load_dwordx4 v[118:121], v[64:65], off
	v_add_co_u32_e32 v100, vcc, s82, v94
	s_nop 0
	v_addc_co_u32_e32 v101, vcc, 0, v95, vcc
	global_load_dwordx4 v[122:125], v[100:101], off
	global_load_dwordx4 v[126:129], v[64:65], off offset:256
	global_load_dwordx4 v[130:133], v[100:101], off offset:256
	v_add_co_u32_e32 v64, vcc, s1, v92
	s_nop 0
	v_addc_co_u32_e32 v65, vcc, 0, v93, vcc
	global_load_dwordx4 v[88:91], v[64:65], off
	v_add_co_u32_e32 v98, vcc, s94, v94
	s_nop 0
	v_addc_co_u32_e32 v99, vcc, 0, v95, vcc
	global_load_dwordx4 v[138:141], v[98:99], off
	global_load_dwordx4 v[80:83], v[64:65], off offset:256
	global_load_dwordx4 v[84:87], v[98:99], off offset:256
	v_add_co_u32_e32 v64, vcc, s4, v92
	s_nop 0
	v_addc_co_u32_e32 v65, vcc, 0, v93, vcc
	global_load_dwordx4 v[72:75], v[64:65], off
	v_add_co_u32_e32 v96, vcc, s51, v94
	s_nop 0
	v_addc_co_u32_e32 v97, vcc, 0, v95, vcc
	global_load_dwordx4 v[76:79], v[96:97], off
	s_nop 0
	global_load_dwordx4 v[64:67], v[64:65], off offset:256
	s_nop 0
	global_load_dwordx4 v[68:71], v[96:97], off offset:256
	s_waitcnt vmcnt(15)
	v_lshlrev_b32_e32 v144, 16, v102
	s_waitcnt vmcnt(14)
	v_lshlrev_b32_e32 v134, 16, v106
	v_and_b32_e32 v135, 0xffff0000, v106
	v_lshlrev_b32_e32 v106, 16, v107
	v_and_b32_e32 v107, 0xffff0000, v107
	v_and_b32_e32 v145, 0xffff0000, v102
	v_lshlrev_b32_e32 v102, 16, v103
	v_and_b32_e32 v103, 0xffff0000, v103
	v_lshlrev_b32_e32 v142, 16, v108
	v_and_b32_e32 v143, 0xffff0000, v108
	v_lshlrev_b32_e32 v108, 16, v109
	v_and_b32_e32 v109, 0xffff0000, v109
	v_pk_fma_f32 v[62:63], v[62:63], v[102:103], v[106:107]
	v_lshlrev_b32_e32 v102, 16, v104
	v_and_b32_e32 v103, 0xffff0000, v104
	v_lshlrev_b32_e32 v104, 16, v105
	v_and_b32_e32 v105, 0xffff0000, v105
	v_pk_fma_f32 v[60:61], v[60:61], v[144:145], v[134:135]
	v_pk_fma_f32 v[104:105], v[58:59], v[104:105], v[108:109]
	v_pk_fma_f32 v[58:59], v[56:57], v[102:103], v[142:143]
	v_cvt_pk_bf16_f32 v56, v60, v61
	v_cvt_pk_bf16_f32 v57, v62, v63
	v_cvt_pk_bf16_f32 v58, v58, v59
	v_cvt_pk_bf16_f32 v59, v104, v105
	global_store_dwordx4 v[94:95], v[56:59], off
	s_waitcnt vmcnt(14)
	v_lshlrev_b32_e32 v102, 16, v110
	v_and_b32_e32 v103, 0xffff0000, v110
	s_waitcnt vmcnt(13)
	v_lshlrev_b32_e32 v56, 16, v114
	v_and_b32_e32 v57, 0xffff0000, v114
	v_lshlrev_b32_e32 v58, 16, v115
	v_and_b32_e32 v59, 0xffff0000, v115
	v_lshlrev_b32_e32 v104, 16, v111
	v_and_b32_e32 v105, 0xffff0000, v111
	v_lshlrev_b32_e32 v60, 16, v116
	v_and_b32_e32 v61, 0xffff0000, v116
	v_lshlrev_b32_e32 v62, 16, v117
	v_and_b32_e32 v63, 0xffff0000, v117
	v_pk_fma_f32 v[54:55], v[54:55], v[104:105], v[58:59]
	v_pk_fma_f32 v[52:53], v[52:53], v[102:103], v[56:57]
	v_lshlrev_b32_e32 v56, 16, v112
	v_and_b32_e32 v57, 0xffff0000, v112
	v_lshlrev_b32_e32 v58, 16, v113
	v_and_b32_e32 v59, 0xffff0000, v113
	v_pk_fma_f32 v[58:59], v[50:51], v[58:59], v[62:63]
	v_pk_fma_f32 v[50:51], v[48:49], v[56:57], v[60:61]
	v_cvt_pk_bf16_f32 v48, v52, v53
	v_cvt_pk_bf16_f32 v49, v54, v55
	v_cvt_pk_bf16_f32 v50, v50, v51
	v_cvt_pk_bf16_f32 v51, v58, v59
	global_store_dwordx4 v[94:95], v[48:51], off offset:256
	s_mov_b64 s[4:5], -1
	s_and_b64 vcc, exec, s[2:3]
	s_waitcnt lgkmcnt(0)
	s_waitcnt vmcnt(13)
	v_lshlrev_b32_e32 v56, 16, v118
	v_and_b32_e32 v57, 0xffff0000, v118
	v_lshlrev_b32_e32 v58, 16, v119
	v_and_b32_e32 v59, 0xffff0000, v119
	s_waitcnt vmcnt(12)
	v_lshlrev_b32_e32 v48, 16, v122
	v_and_b32_e32 v49, 0xffff0000, v122
	v_lshlrev_b32_e32 v50, 16, v123
	v_and_b32_e32 v51, 0xffff0000, v123
	v_lshlrev_b32_e32 v52, 16, v124
	v_and_b32_e32 v53, 0xffff0000, v124
	v_lshlrev_b32_e32 v54, 16, v125
	v_and_b32_e32 v55, 0xffff0000, v125
	v_pk_fma_f32 v[46:47], v[46:47], v[58:59], v[50:51]
	v_pk_fma_f32 v[44:45], v[44:45], v[56:57], v[48:49]
	v_lshlrev_b32_e32 v48, 16, v120
	v_and_b32_e32 v49, 0xffff0000, v120
	v_lshlrev_b32_e32 v50, 16, v121
	v_and_b32_e32 v51, 0xffff0000, v121
	v_pk_fma_f32 v[50:51], v[42:43], v[50:51], v[54:55]
	v_pk_fma_f32 v[42:43], v[40:41], v[48:49], v[52:53]
	v_cvt_pk_bf16_f32 v40, v44, v45
	v_cvt_pk_bf16_f32 v41, v46, v47
	v_cvt_pk_bf16_f32 v42, v42, v43
	v_cvt_pk_bf16_f32 v43, v50, v51
	global_store_dwordx4 v[100:101], v[40:43], off
	s_waitcnt vmcnt(12)
	v_lshlrev_b32_e32 v48, 16, v126
	v_and_b32_e32 v49, 0xffff0000, v126
	s_waitcnt vmcnt(11)
	v_lshlrev_b32_e32 v40, 16, v130
	v_and_b32_e32 v41, 0xffff0000, v130
	v_lshlrev_b32_e32 v42, 16, v131
	v_and_b32_e32 v43, 0xffff0000, v131
	v_lshlrev_b32_e32 v50, 16, v127
	v_and_b32_e32 v51, 0xffff0000, v127
	v_lshlrev_b32_e32 v44, 16, v132
	v_and_b32_e32 v45, 0xffff0000, v132
	v_lshlrev_b32_e32 v46, 16, v133
	v_and_b32_e32 v47, 0xffff0000, v133
	v_pk_fma_f32 v[38:39], v[38:39], v[50:51], v[42:43]
	v_pk_fma_f32 v[36:37], v[36:37], v[48:49], v[40:41]
	v_lshlrev_b32_e32 v40, 16, v128
	v_and_b32_e32 v41, 0xffff0000, v128
	v_lshlrev_b32_e32 v42, 16, v129
	v_and_b32_e32 v43, 0xffff0000, v129
	v_pk_fma_f32 v[42:43], v[34:35], v[42:43], v[46:47]
	v_pk_fma_f32 v[34:35], v[32:33], v[40:41], v[44:45]
	v_cvt_pk_bf16_f32 v32, v36, v37
	v_cvt_pk_bf16_f32 v33, v38, v39
	v_cvt_pk_bf16_f32 v34, v34, v35
	v_cvt_pk_bf16_f32 v35, v42, v43
	global_store_dwordx4 v[100:101], v[32:35], off offset:256
	s_waitcnt vmcnt(11)
	v_lshlrev_b32_e32 v40, 16, v88
	v_and_b32_e32 v41, 0xffff0000, v88
	s_waitcnt vmcnt(10)
	v_lshlrev_b32_e32 v32, 16, v138
	v_and_b32_e32 v33, 0xffff0000, v138
	v_lshlrev_b32_e32 v34, 16, v139
	v_and_b32_e32 v35, 0xffff0000, v139
	v_lshlrev_b32_e32 v42, 16, v89
	v_and_b32_e32 v43, 0xffff0000, v89
	v_lshlrev_b32_e32 v36, 16, v140
	v_and_b32_e32 v37, 0xffff0000, v140
	v_lshlrev_b32_e32 v38, 16, v141
	v_and_b32_e32 v39, 0xffff0000, v141
	v_pk_fma_f32 v[30:31], v[30:31], v[42:43], v[34:35]
	v_pk_fma_f32 v[28:29], v[28:29], v[40:41], v[32:33]
	v_lshlrev_b32_e32 v32, 16, v90
	v_and_b32_e32 v33, 0xffff0000, v90
	v_lshlrev_b32_e32 v34, 16, v91
	v_and_b32_e32 v35, 0xffff0000, v91
	v_pk_fma_f32 v[34:35], v[26:27], v[34:35], v[38:39]
	v_pk_fma_f32 v[26:27], v[24:25], v[32:33], v[36:37]
	v_cvt_pk_bf16_f32 v24, v28, v29
	v_cvt_pk_bf16_f32 v25, v30, v31
	v_cvt_pk_bf16_f32 v26, v26, v27
	v_cvt_pk_bf16_f32 v27, v34, v35
	global_store_dwordx4 v[98:99], v[24:27], off
	s_waitcnt vmcnt(10)
	v_lshlrev_b32_e32 v32, 16, v80
	v_and_b32_e32 v33, 0xffff0000, v80
	s_waitcnt vmcnt(9)
	v_lshlrev_b32_e32 v24, 16, v84
	v_and_b32_e32 v25, 0xffff0000, v84
	v_lshlrev_b32_e32 v26, 16, v85
	v_and_b32_e32 v27, 0xffff0000, v85
	v_lshlrev_b32_e32 v34, 16, v81
	v_and_b32_e32 v35, 0xffff0000, v81
	v_lshlrev_b32_e32 v28, 16, v86
	v_and_b32_e32 v29, 0xffff0000, v86
	v_lshlrev_b32_e32 v30, 16, v87
	v_and_b32_e32 v31, 0xffff0000, v87
	v_pk_fma_f32 v[22:23], v[22:23], v[34:35], v[26:27]
	v_pk_fma_f32 v[20:21], v[20:21], v[32:33], v[24:25]
	v_lshlrev_b32_e32 v24, 16, v82
	v_and_b32_e32 v25, 0xffff0000, v82
	v_lshlrev_b32_e32 v26, 16, v83
	v_and_b32_e32 v27, 0xffff0000, v83
	v_pk_fma_f32 v[26:27], v[18:19], v[26:27], v[30:31]
	v_pk_fma_f32 v[18:19], v[16:17], v[24:25], v[28:29]
	v_cvt_pk_bf16_f32 v16, v20, v21
	v_cvt_pk_bf16_f32 v17, v22, v23
	v_cvt_pk_bf16_f32 v18, v18, v19
	v_cvt_pk_bf16_f32 v19, v26, v27
	global_store_dwordx4 v[98:99], v[16:19], off offset:256
	s_waitcnt vmcnt(9)
	v_lshlrev_b32_e32 v24, 16, v72
	v_and_b32_e32 v25, 0xffff0000, v72
	s_waitcnt vmcnt(8)
	v_lshlrev_b32_e32 v16, 16, v76
	v_and_b32_e32 v17, 0xffff0000, v76
	v_lshlrev_b32_e32 v18, 16, v77
	v_and_b32_e32 v19, 0xffff0000, v77
	v_lshlrev_b32_e32 v26, 16, v73
	v_and_b32_e32 v27, 0xffff0000, v73
	v_lshlrev_b32_e32 v20, 16, v78
	v_and_b32_e32 v21, 0xffff0000, v78
	v_lshlrev_b32_e32 v22, 16, v79
	v_and_b32_e32 v23, 0xffff0000, v79
	v_pk_fma_f32 v[14:15], v[14:15], v[26:27], v[18:19]
	v_pk_fma_f32 v[12:13], v[12:13], v[24:25], v[16:17]
	v_lshlrev_b32_e32 v16, 16, v74
	v_and_b32_e32 v17, 0xffff0000, v74
	v_lshlrev_b32_e32 v18, 16, v75
	v_and_b32_e32 v19, 0xffff0000, v75
	v_pk_fma_f32 v[18:19], v[10:11], v[18:19], v[22:23]
	v_pk_fma_f32 v[10:11], v[8:9], v[16:17], v[20:21]
	v_cvt_pk_bf16_f32 v8, v12, v13
	v_cvt_pk_bf16_f32 v9, v14, v15
	v_cvt_pk_bf16_f32 v10, v10, v11
	v_cvt_pk_bf16_f32 v11, v18, v19
	global_store_dwordx4 v[96:97], v[8:11], off
	s_waitcnt vmcnt(8)
	v_lshlrev_b32_e32 v16, 16, v64
	v_and_b32_e32 v17, 0xffff0000, v64
	s_waitcnt vmcnt(7)
	v_lshlrev_b32_e32 v8, 16, v68
	v_and_b32_e32 v9, 0xffff0000, v68
	v_lshlrev_b32_e32 v10, 16, v69
	v_and_b32_e32 v11, 0xffff0000, v69
	v_lshlrev_b32_e32 v18, 16, v65
	v_and_b32_e32 v19, 0xffff0000, v65
	v_lshlrev_b32_e32 v12, 16, v70
	v_and_b32_e32 v13, 0xffff0000, v70
	v_lshlrev_b32_e32 v14, 16, v71
	v_and_b32_e32 v15, 0xffff0000, v71
	v_pk_fma_f32 v[6:7], v[6:7], v[18:19], v[10:11]
	v_pk_fma_f32 v[4:5], v[4:5], v[16:17], v[8:9]
	v_lshlrev_b32_e32 v8, 16, v66
	v_and_b32_e32 v9, 0xffff0000, v66
	v_lshlrev_b32_e32 v10, 16, v67
	v_and_b32_e32 v11, 0xffff0000, v67
	v_pk_fma_f32 v[10:11], v[2:3], v[10:11], v[14:15]
	v_pk_fma_f32 v[2:3], v[0:1], v[8:9], v[12:13]
	v_cvt_pk_bf16_f32 v0, v4, v5
	v_cvt_pk_bf16_f32 v1, v6, v7
	v_cvt_pk_bf16_f32 v2, v2, v3
	v_cvt_pk_bf16_f32 v3, v10, v11
	global_store_dwordx4 v[96:97], v[0:3], off offset:256
	s_nop 1
	v_lshl_add_u64 v[0:1], v[92:93], 0, s[24:25]
	v_lshl_add_u64 v[2:3], v[94:95], 0, s[78:79]
	s_cbranch_vccnz .LBB0_683
	s_andn2_b64 vcc, exec, s[10:11]
	s_cbranch_vccnz .LBB0_682
	s_barrier
	s_branch .LBB0_682

.LBB0_724:
	s_lshl_b32 s20, s44, 8
	v_mbcnt_lo_u32_b32 v129, -1, 0
	v_mbcnt_hi_u32_b32 v129, -1, v129
	s_add_i32 s20, s20, s37
	v_and_or_b32 v128, v129, 15, s20
	s_lshl_b32 s20, s45, 8
	v_ashrrev_i32_e32 v129, 1, v129
	s_or_b32 s20, s20, s38
	v_and_b32_e32 v129, -8, v129
	v_add_u32_e32 v130, s20, v129
	v_ashrrev_i32_e32 v129, 31, v128
	v_mov_b64_e32 v[132:133], s[14:15]
	v_ashrrev_i32_e32 v131, 31, v130
	v_mad_i64_i32 v[132:133], s[20:21], v128, s72, v[132:133]
	v_lshlrev_b64 v[130:131], 1, v[130:131]
	v_lshlrev_b64 v[128:129], 11, v[128:129]
	v_lshl_add_u64 v[196:197], v[132:133], 0, v[130:131]
	v_lshl_add_u64 v[128:129], s[12:13], 0, v[128:129]
	v_lshl_add_u64 v[198:199], v[128:129], 0, v[130:131]
	global_load_dwordx4 v[204:207], v[196:197], off
	global_load_dwordx4 v[220:223], v[198:199], off
	global_load_dwordx4 v[174:177], v[196:197], off offset:256
	global_load_dwordx4 v[182:185], v[198:199], off offset:256
	v_add_co_u32_e32 v128, vcc, s51, v196
	s_mov_b32 s20, 0x48000
	s_nop 0
	v_addc_co_u32_e32 v129, vcc, 0, v197, vcc
	global_load_dwordx4 v[170:173], v[128:129], off
	v_add_co_u32_e32 v218, vcc, s82, v198
	s_mov_b64 s[22:23], 0xc0000
	s_nop 0
	v_addc_co_u32_e32 v219, vcc, 0, v199, vcc
	global_load_dwordx4 v[178:181], v[218:219], off
	global_load_dwordx4 v[158:161], v[128:129], off offset:256
	global_load_dwordx4 v[166:169], v[218:219], off offset:256
	v_add_co_u32_e32 v128, vcc, s1, v196
	v_addc_co_u32_e32 v129, vcc, 0, v197, vcc
	global_load_dwordx4 v[154:157], v[128:129], off
	v_add_co_u32_e32 v216, vcc, s94, v198
	s_nop 0
	v_addc_co_u32_e32 v217, vcc, 0, v199, vcc
	global_load_dwordx4 v[162:165], v[216:217], off
	global_load_dwordx4 v[142:145], v[128:129], off offset:256
	global_load_dwordx4 v[150:153], v[216:217], off offset:256
	v_add_co_u32_e32 v128, vcc, s20, v196
	s_nop 0
	v_addc_co_u32_e32 v129, vcc, 0, v197, vcc
	global_load_dwordx4 v[132:135], v[128:129], off
	v_add_co_u32_e32 v200, vcc, s51, v198
	s_nop 0
	v_addc_co_u32_e32 v201, vcc, 0, v199, vcc
	global_load_dwordx4 v[146:149], v[200:201], off
	s_nop 0
	global_load_dwordx4 v[128:131], v[128:129], off offset:256
	s_nop 0
	global_load_dwordx4 v[138:141], v[200:201], off offset:256
	s_waitcnt vmcnt(14)
	v_lshlrev_b32_e32 v208, 16, v220
	v_and_b32_e32 v209, 0xffff0000, v220
	v_lshlrev_b32_e32 v210, 16, v221
	v_and_b32_e32 v211, 0xffff0000, v221
	v_lshlrev_b32_e32 v220, 16, v204
	v_and_b32_e32 v221, 0xffff0000, v204
	v_lshlrev_b32_e32 v204, 16, v205
	v_and_b32_e32 v205, 0xffff0000, v205
	v_lshlrev_b32_e32 v212, 16, v222
	v_and_b32_e32 v213, 0xffff0000, v222
	v_lshlrev_b32_e32 v214, 16, v223
	v_and_b32_e32 v215, 0xffff0000, v223
	v_pk_fma_f32 v[126:127], v[126:127], v[204:205], v[210:211]
	v_lshlrev_b32_e32 v204, 16, v206
	v_and_b32_e32 v205, 0xffff0000, v206
	v_lshlrev_b32_e32 v206, 16, v207
	v_and_b32_e32 v207, 0xffff0000, v207
	v_pk_fma_f32 v[124:125], v[124:125], v[220:221], v[208:209]
	v_pk_fma_f32 v[206:207], v[122:123], v[206:207], v[214:215]
	v_pk_fma_f32 v[122:123], v[120:121], v[204:205], v[212:213]
	v_cvt_pk_bf16_f32 v120, v124, v125
	v_cvt_pk_bf16_f32 v121, v126, v127
	v_cvt_pk_bf16_f32 v122, v122, v123
	v_cvt_pk_bf16_f32 v123, v206, v207
	global_store_dwordx4 v[198:199], v[120:123], off
	s_waitcnt vmcnt(13)
	v_lshlrev_b32_e32 v124, 16, v184
	v_and_b32_e32 v125, 0xffff0000, v184
	v_lshlrev_b32_e32 v120, 16, v182
	v_and_b32_e32 v121, 0xffff0000, v182
	v_lshlrev_b32_e32 v122, 16, v183
	v_and_b32_e32 v123, 0xffff0000, v183
	v_lshlrev_b32_e32 v182, 16, v174
	v_and_b32_e32 v183, 0xffff0000, v174
	v_lshlrev_b32_e32 v174, 16, v175
	v_and_b32_e32 v175, 0xffff0000, v175
	v_lshlrev_b32_e32 v126, 16, v185
	v_and_b32_e32 v127, 0xffff0000, v185
	v_pk_fma_f32 v[118:119], v[118:119], v[174:175], v[122:123]
	v_pk_fma_f32 v[116:117], v[116:117], v[182:183], v[120:121]
	v_lshlrev_b32_e32 v120, 16, v176
	v_and_b32_e32 v121, 0xffff0000, v176
	v_lshlrev_b32_e32 v122, 16, v177
	v_and_b32_e32 v123, 0xffff0000, v177
	v_pk_fma_f32 v[122:123], v[114:115], v[122:123], v[126:127]
	v_pk_fma_f32 v[114:115], v[112:113], v[120:121], v[124:125]
	v_cvt_pk_bf16_f32 v112, v116, v117
	v_cvt_pk_bf16_f32 v113, v118, v119
	v_cvt_pk_bf16_f32 v114, v114, v115
	v_cvt_pk_bf16_f32 v115, v122, v123
	global_store_dwordx4 v[198:199], v[112:115], off offset:256
	s_waitcnt vmcnt(13)
	v_lshlrev_b32_e32 v120, 16, v170
	v_and_b32_e32 v121, 0xffff0000, v170
	s_waitcnt vmcnt(12)
	v_lshlrev_b32_e32 v112, 16, v178
	v_and_b32_e32 v113, 0xffff0000, v178
	v_lshlrev_b32_e32 v114, 16, v179
	v_and_b32_e32 v115, 0xffff0000, v179
	v_lshlrev_b32_e32 v122, 16, v171
	v_and_b32_e32 v123, 0xffff0000, v171
	v_lshlrev_b32_e32 v116, 16, v180
	v_and_b32_e32 v117, 0xffff0000, v180
	v_lshlrev_b32_e32 v118, 16, v181
	v_and_b32_e32 v119, 0xffff0000, v181
	v_pk_fma_f32 v[110:111], v[110:111], v[122:123], v[114:115]
	v_pk_fma_f32 v[108:109], v[108:109], v[120:121], v[112:113]
	v_lshlrev_b32_e32 v112, 16, v172
	v_and_b32_e32 v113, 0xffff0000, v172
	v_lshlrev_b32_e32 v114, 16, v173
	v_and_b32_e32 v115, 0xffff0000, v173
	v_pk_fma_f32 v[114:115], v[106:107], v[114:115], v[118:119]
	v_pk_fma_f32 v[106:107], v[104:105], v[112:113], v[116:117]
	v_cvt_pk_bf16_f32 v104, v108, v109
	v_cvt_pk_bf16_f32 v105, v110, v111
	v_cvt_pk_bf16_f32 v106, v106, v107
	v_cvt_pk_bf16_f32 v107, v114, v115
	global_store_dwordx4 v[218:219], v[104:107], off
	s_waitcnt vmcnt(12)
	v_lshlrev_b32_e32 v112, 16, v158
	v_and_b32_e32 v113, 0xffff0000, v158
	s_waitcnt vmcnt(11)
	v_lshlrev_b32_e32 v104, 16, v166
	v_and_b32_e32 v105, 0xffff0000, v166
	v_lshlrev_b32_e32 v106, 16, v167
	v_and_b32_e32 v107, 0xffff0000, v167
	v_lshlrev_b32_e32 v114, 16, v159
	v_and_b32_e32 v115, 0xffff0000, v159
	v_lshlrev_b32_e32 v108, 16, v168
	v_and_b32_e32 v109, 0xffff0000, v168
	v_lshlrev_b32_e32 v110, 16, v169
	v_and_b32_e32 v111, 0xffff0000, v169
	v_pk_fma_f32 v[102:103], v[102:103], v[114:115], v[106:107]
	v_pk_fma_f32 v[100:101], v[100:101], v[112:113], v[104:105]
	v_lshlrev_b32_e32 v104, 16, v160
	v_and_b32_e32 v105, 0xffff0000, v160
	v_lshlrev_b32_e32 v106, 16, v161
	v_and_b32_e32 v107, 0xffff0000, v161
	v_pk_fma_f32 v[106:107], v[98:99], v[106:107], v[110:111]
	v_pk_fma_f32 v[98:99], v[96:97], v[104:105], v[108:109]
	v_cvt_pk_bf16_f32 v96, v100, v101
	v_cvt_pk_bf16_f32 v97, v102, v103
	v_cvt_pk_bf16_f32 v98, v98, v99
	v_cvt_pk_bf16_f32 v99, v106, v107
	global_store_dwordx4 v[218:219], v[96:99], off offset:256
	s_waitcnt lgkmcnt(0)
	s_waitcnt vmcnt(11)
	v_lshlrev_b32_e32 v104, 16, v154
	v_and_b32_e32 v105, 0xffff0000, v154
	s_waitcnt vmcnt(10)
	v_lshlrev_b32_e32 v96, 16, v162
	v_and_b32_e32 v97, 0xffff0000, v162
	v_lshlrev_b32_e32 v98, 16, v163
	v_and_b32_e32 v99, 0xffff0000, v163
	v_lshlrev_b32_e32 v106, 16, v155
	v_and_b32_e32 v107, 0xffff0000, v155
	v_lshlrev_b32_e32 v100, 16, v164
	v_and_b32_e32 v101, 0xffff0000, v164
	v_lshlrev_b32_e32 v102, 16, v165
	v_and_b32_e32 v103, 0xffff0000, v165
	v_pk_fma_f32 v[94:95], v[94:95], v[106:107], v[98:99]
	v_pk_fma_f32 v[92:93], v[92:93], v[104:105], v[96:97]
	v_lshlrev_b32_e32 v96, 16, v156
	v_and_b32_e32 v97, 0xffff0000, v156
	v_lshlrev_b32_e32 v98, 16, v157
	v_and_b32_e32 v99, 0xffff0000, v157
	v_pk_fma_f32 v[98:99], v[90:91], v[98:99], v[102:103]
	v_pk_fma_f32 v[90:91], v[88:89], v[96:97], v[100:101]
	v_cvt_pk_bf16_f32 v88, v92, v93
	v_cvt_pk_bf16_f32 v89, v94, v95
	v_cvt_pk_bf16_f32 v90, v90, v91
	v_cvt_pk_bf16_f32 v91, v98, v99
	global_store_dwordx4 v[216:217], v[88:91], off
	s_waitcnt vmcnt(10)
	v_lshlrev_b32_e32 v96, 16, v142
	v_and_b32_e32 v97, 0xffff0000, v142
	s_waitcnt vmcnt(9)
	v_lshlrev_b32_e32 v88, 16, v150
	v_and_b32_e32 v89, 0xffff0000, v150
	v_lshlrev_b32_e32 v90, 16, v151
	v_and_b32_e32 v91, 0xffff0000, v151
	v_lshlrev_b32_e32 v98, 16, v143
	v_and_b32_e32 v99, 0xffff0000, v143
	v_lshlrev_b32_e32 v92, 16, v152
	v_and_b32_e32 v93, 0xffff0000, v152
	v_lshlrev_b32_e32 v94, 16, v153
	v_and_b32_e32 v95, 0xffff0000, v153
	v_pk_fma_f32 v[86:87], v[86:87], v[98:99], v[90:91]
	v_pk_fma_f32 v[84:85], v[84:85], v[96:97], v[88:89]
	v_lshlrev_b32_e32 v88, 16, v144
	v_and_b32_e32 v89, 0xffff0000, v144
	v_lshlrev_b32_e32 v90, 16, v145
	v_and_b32_e32 v91, 0xffff0000, v145
	v_pk_fma_f32 v[90:91], v[82:83], v[90:91], v[94:95]
	v_pk_fma_f32 v[82:83], v[80:81], v[88:89], v[92:93]
	v_cvt_pk_bf16_f32 v80, v84, v85
	v_cvt_pk_bf16_f32 v81, v86, v87
	v_cvt_pk_bf16_f32 v82, v82, v83
	v_cvt_pk_bf16_f32 v83, v90, v91
	global_store_dwordx4 v[216:217], v[80:83], off offset:256
	s_waitcnt vmcnt(9)
	v_lshlrev_b32_e32 v88, 16, v132
	v_and_b32_e32 v89, 0xffff0000, v132
	s_waitcnt vmcnt(8)
	v_lshlrev_b32_e32 v80, 16, v146
	v_and_b32_e32 v81, 0xffff0000, v146
	v_lshlrev_b32_e32 v82, 16, v147
	v_and_b32_e32 v83, 0xffff0000, v147
	v_lshlrev_b32_e32 v90, 16, v133
	v_and_b32_e32 v91, 0xffff0000, v133
	v_lshlrev_b32_e32 v84, 16, v148
	v_and_b32_e32 v85, 0xffff0000, v148
	v_lshlrev_b32_e32 v86, 16, v149
	v_and_b32_e32 v87, 0xffff0000, v149
	v_pk_fma_f32 v[78:79], v[78:79], v[90:91], v[82:83]
	v_pk_fma_f32 v[76:77], v[76:77], v[88:89], v[80:81]
	v_lshlrev_b32_e32 v80, 16, v134
	v_and_b32_e32 v81, 0xffff0000, v134
	v_lshlrev_b32_e32 v82, 16, v135
	v_and_b32_e32 v83, 0xffff0000, v135
	v_pk_fma_f32 v[82:83], v[74:75], v[82:83], v[86:87]
	v_pk_fma_f32 v[74:75], v[72:73], v[80:81], v[84:85]
	v_cvt_pk_bf16_f32 v72, v76, v77
	v_cvt_pk_bf16_f32 v73, v78, v79
	v_cvt_pk_bf16_f32 v74, v74, v75
	v_cvt_pk_bf16_f32 v75, v82, v83
	global_store_dwordx4 v[200:201], v[72:75], off
	s_waitcnt vmcnt(8)
	v_lshlrev_b32_e32 v80, 16, v128
	v_and_b32_e32 v81, 0xffff0000, v128
	s_waitcnt vmcnt(7)
	v_lshlrev_b32_e32 v72, 16, v138
	v_and_b32_e32 v73, 0xffff0000, v138
	v_lshlrev_b32_e32 v74, 16, v139
	v_and_b32_e32 v75, 0xffff0000, v139
	v_lshlrev_b32_e32 v82, 16, v129
	v_and_b32_e32 v83, 0xffff0000, v129
	v_lshlrev_b32_e32 v76, 16, v140
	v_and_b32_e32 v77, 0xffff0000, v140
	v_lshlrev_b32_e32 v78, 16, v141
	v_and_b32_e32 v79, 0xffff0000, v141
	v_pk_fma_f32 v[70:71], v[70:71], v[82:83], v[74:75]
	v_pk_fma_f32 v[68:69], v[68:69], v[80:81], v[72:73]
	v_lshlrev_b32_e32 v72, 16, v130
	v_and_b32_e32 v73, 0xffff0000, v130
	v_lshlrev_b32_e32 v74, 16, v131
	v_and_b32_e32 v75, 0xffff0000, v131
	v_pk_fma_f32 v[74:75], v[66:67], v[74:75], v[78:79]
	v_pk_fma_f32 v[66:67], v[64:65], v[72:73], v[76:77]
	v_cvt_pk_bf16_f32 v64, v68, v69
	v_cvt_pk_bf16_f32 v65, v70, v71
	v_cvt_pk_bf16_f32 v66, v66, v67
	v_cvt_pk_bf16_f32 v67, v74, v75
	v_lshl_add_u64 v[92:93], v[196:197], 0, s[22:23]
	v_lshl_add_u64 v[94:95], v[198:199], 0, s[78:79]
	global_store_dwordx4 v[200:201], v[64:67], off offset:256
	global_load_dwordx4 v[102:105], v[92:93], off
	global_load_dwordx4 v[106:109], v[94:95], off
	global_load_dwordx4 v[110:113], v[92:93], off offset:256
	global_load_dwordx4 v[114:117], v[94:95], off offset:256
	v_add_co_u32_e32 v64, vcc, s51, v92
	v_addc_co_u32_e32 v65, vcc, 0, v93, vcc
	global_load_dwordx4 v[118:121], v[64:65], off
	v_add_co_u32_e32 v100, vcc, s82, v94
	s_nop 0
	v_addc_co_u32_e32 v101, vcc, 0, v95, vcc
	global_load_dwordx4 v[122:125], v[100:101], off
	global_load_dwordx4 v[126:129], v[64:65], off offset:256
	global_load_dwordx4 v[130:133], v[100:101], off offset:256
	v_add_co_u32_e32 v64, vcc, s1, v92
	s_nop 0
	v_addc_co_u32_e32 v65, vcc, 0, v93, vcc
	global_load_dwordx4 v[88:91], v[64:65], off
	v_add_co_u32_e32 v98, vcc, s94, v94
	s_nop 0
	v_addc_co_u32_e32 v99, vcc, 0, v95, vcc
	global_load_dwordx4 v[138:141], v[98:99], off
	global_load_dwordx4 v[80:83], v[64:65], off offset:256
	global_load_dwordx4 v[84:87], v[98:99], off offset:256
	v_add_co_u32_e32 v64, vcc, s20, v92
	s_nop 0
	v_addc_co_u32_e32 v65, vcc, 0, v93, vcc
	global_load_dwordx4 v[72:75], v[64:65], off
	v_add_co_u32_e32 v96, vcc, s51, v94
	s_nop 0
	v_addc_co_u32_e32 v97, vcc, 0, v95, vcc
	global_load_dwordx4 v[76:79], v[96:97], off
	s_nop 0
	global_load_dwordx4 v[64:67], v[64:65], off offset:256
	s_nop 0
	global_load_dwordx4 v[68:71], v[96:97], off offset:256
	s_waitcnt vmcnt(15)
	v_lshlrev_b32_e32 v144, 16, v102
	s_waitcnt vmcnt(14)
	v_lshlrev_b32_e32 v134, 16, v106
	v_and_b32_e32 v135, 0xffff0000, v106
	v_lshlrev_b32_e32 v106, 16, v107
	v_and_b32_e32 v107, 0xffff0000, v107
	v_and_b32_e32 v145, 0xffff0000, v102
	v_lshlrev_b32_e32 v102, 16, v103
	v_and_b32_e32 v103, 0xffff0000, v103
	v_lshlrev_b32_e32 v142, 16, v108
	v_and_b32_e32 v143, 0xffff0000, v108
	v_lshlrev_b32_e32 v108, 16, v109
	v_and_b32_e32 v109, 0xffff0000, v109
	v_pk_fma_f32 v[62:63], v[62:63], v[102:103], v[106:107]
	v_lshlrev_b32_e32 v102, 16, v104
	v_and_b32_e32 v103, 0xffff0000, v104
	v_lshlrev_b32_e32 v104, 16, v105
	v_and_b32_e32 v105, 0xffff0000, v105
	v_pk_fma_f32 v[60:61], v[60:61], v[144:145], v[134:135]
	v_pk_fma_f32 v[104:105], v[58:59], v[104:105], v[108:109]
	v_pk_fma_f32 v[58:59], v[56:57], v[102:103], v[142:143]
	v_cvt_pk_bf16_f32 v56, v60, v61
	v_cvt_pk_bf16_f32 v57, v62, v63
	v_cvt_pk_bf16_f32 v58, v58, v59
	v_cvt_pk_bf16_f32 v59, v104, v105
	global_store_dwordx4 v[94:95], v[56:59], off
	s_waitcnt vmcnt(14)
	v_lshlrev_b32_e32 v102, 16, v110
	v_and_b32_e32 v103, 0xffff0000, v110
	s_waitcnt vmcnt(13)
	v_lshlrev_b32_e32 v56, 16, v114
	v_and_b32_e32 v57, 0xffff0000, v114
	v_lshlrev_b32_e32 v58, 16, v115
	v_and_b32_e32 v59, 0xffff0000, v115
	v_lshlrev_b32_e32 v104, 16, v111
	v_and_b32_e32 v105, 0xffff0000, v111
	v_lshlrev_b32_e32 v60, 16, v116
	v_and_b32_e32 v61, 0xffff0000, v116
	v_lshlrev_b32_e32 v62, 16, v117
	v_and_b32_e32 v63, 0xffff0000, v117
	v_pk_fma_f32 v[54:55], v[54:55], v[104:105], v[58:59]
	v_pk_fma_f32 v[52:53], v[52:53], v[102:103], v[56:57]
	v_lshlrev_b32_e32 v56, 16, v112
	v_and_b32_e32 v57, 0xffff0000, v112
	v_lshlrev_b32_e32 v58, 16, v113
	v_and_b32_e32 v59, 0xffff0000, v113
	v_pk_fma_f32 v[58:59], v[50:51], v[58:59], v[62:63]
	v_pk_fma_f32 v[50:51], v[48:49], v[56:57], v[60:61]
	v_cvt_pk_bf16_f32 v48, v52, v53
	v_cvt_pk_bf16_f32 v49, v54, v55
	v_cvt_pk_bf16_f32 v50, v50, v51
	v_cvt_pk_bf16_f32 v51, v58, v59
	global_store_dwordx4 v[94:95], v[48:51], off offset:256
	s_mov_b64 s[20:21], -1
	s_and_b64 vcc, exec, s[2:3]
	s_waitcnt lgkmcnt(0)
	s_waitcnt vmcnt(13)
	v_lshlrev_b32_e32 v56, 16, v118
	v_and_b32_e32 v57, 0xffff0000, v118
	v_lshlrev_b32_e32 v58, 16, v119
	v_and_b32_e32 v59, 0xffff0000, v119
	s_waitcnt vmcnt(12)
	v_lshlrev_b32_e32 v48, 16, v122
	v_and_b32_e32 v49, 0xffff0000, v122
	v_lshlrev_b32_e32 v50, 16, v123
	v_and_b32_e32 v51, 0xffff0000, v123
	v_lshlrev_b32_e32 v52, 16, v124
	v_and_b32_e32 v53, 0xffff0000, v124
	v_lshlrev_b32_e32 v54, 16, v125
	v_and_b32_e32 v55, 0xffff0000, v125
	v_pk_fma_f32 v[46:47], v[46:47], v[58:59], v[50:51]
	v_pk_fma_f32 v[44:45], v[44:45], v[56:57], v[48:49]
	v_lshlrev_b32_e32 v48, 16, v120
	v_and_b32_e32 v49, 0xffff0000, v120
	v_lshlrev_b32_e32 v50, 16, v121
	v_and_b32_e32 v51, 0xffff0000, v121
	v_pk_fma_f32 v[50:51], v[42:43], v[50:51], v[54:55]
	v_pk_fma_f32 v[42:43], v[40:41], v[48:49], v[52:53]
	v_cvt_pk_bf16_f32 v40, v44, v45
	v_cvt_pk_bf16_f32 v41, v46, v47
	v_cvt_pk_bf16_f32 v42, v42, v43
	v_cvt_pk_bf16_f32 v43, v50, v51
	global_store_dwordx4 v[100:101], v[40:43], off
	s_waitcnt vmcnt(12)
	v_lshlrev_b32_e32 v48, 16, v126
	v_and_b32_e32 v49, 0xffff0000, v126
	s_waitcnt vmcnt(11)
	v_lshlrev_b32_e32 v40, 16, v130
	v_and_b32_e32 v41, 0xffff0000, v130
	v_lshlrev_b32_e32 v42, 16, v131
	v_and_b32_e32 v43, 0xffff0000, v131
	v_lshlrev_b32_e32 v50, 16, v127
	v_and_b32_e32 v51, 0xffff0000, v127
	v_lshlrev_b32_e32 v44, 16, v132
	v_and_b32_e32 v45, 0xffff0000, v132
	v_lshlrev_b32_e32 v46, 16, v133
	v_and_b32_e32 v47, 0xffff0000, v133
	v_pk_fma_f32 v[38:39], v[38:39], v[50:51], v[42:43]
	v_pk_fma_f32 v[36:37], v[36:37], v[48:49], v[40:41]
	v_lshlrev_b32_e32 v40, 16, v128
	v_and_b32_e32 v41, 0xffff0000, v128
	v_lshlrev_b32_e32 v42, 16, v129
	v_and_b32_e32 v43, 0xffff0000, v129
	v_pk_fma_f32 v[42:43], v[34:35], v[42:43], v[46:47]
	v_pk_fma_f32 v[34:35], v[32:33], v[40:41], v[44:45]
	v_cvt_pk_bf16_f32 v32, v36, v37
	v_cvt_pk_bf16_f32 v33, v38, v39
	v_cvt_pk_bf16_f32 v34, v34, v35
	v_cvt_pk_bf16_f32 v35, v42, v43
	global_store_dwordx4 v[100:101], v[32:35], off offset:256
	s_waitcnt vmcnt(11)
	v_lshlrev_b32_e32 v40, 16, v88
	v_and_b32_e32 v41, 0xffff0000, v88
	s_waitcnt vmcnt(10)
	v_lshlrev_b32_e32 v32, 16, v138
	v_and_b32_e32 v33, 0xffff0000, v138
	v_lshlrev_b32_e32 v34, 16, v139
	v_and_b32_e32 v35, 0xffff0000, v139
	v_lshlrev_b32_e32 v42, 16, v89
	v_and_b32_e32 v43, 0xffff0000, v89
	v_lshlrev_b32_e32 v36, 16, v140
	v_and_b32_e32 v37, 0xffff0000, v140
	v_lshlrev_b32_e32 v38, 16, v141
	v_and_b32_e32 v39, 0xffff0000, v141
	v_pk_fma_f32 v[30:31], v[30:31], v[42:43], v[34:35]
	v_pk_fma_f32 v[28:29], v[28:29], v[40:41], v[32:33]
	v_lshlrev_b32_e32 v32, 16, v90
	v_and_b32_e32 v33, 0xffff0000, v90
	v_lshlrev_b32_e32 v34, 16, v91
	v_and_b32_e32 v35, 0xffff0000, v91
	v_pk_fma_f32 v[34:35], v[26:27], v[34:35], v[38:39]
	v_pk_fma_f32 v[26:27], v[24:25], v[32:33], v[36:37]
	v_cvt_pk_bf16_f32 v24, v28, v29
	v_cvt_pk_bf16_f32 v25, v30, v31
	v_cvt_pk_bf16_f32 v26, v26, v27
	v_cvt_pk_bf16_f32 v27, v34, v35
	global_store_dwordx4 v[98:99], v[24:27], off
	s_waitcnt vmcnt(10)
	v_lshlrev_b32_e32 v32, 16, v80
	v_and_b32_e32 v33, 0xffff0000, v80
	s_waitcnt vmcnt(9)
	v_lshlrev_b32_e32 v24, 16, v84
	v_and_b32_e32 v25, 0xffff0000, v84
	v_lshlrev_b32_e32 v26, 16, v85
	v_and_b32_e32 v27, 0xffff0000, v85
	v_lshlrev_b32_e32 v34, 16, v81
	v_and_b32_e32 v35, 0xffff0000, v81
	v_lshlrev_b32_e32 v28, 16, v86
	v_and_b32_e32 v29, 0xffff0000, v86
	v_lshlrev_b32_e32 v30, 16, v87
	v_and_b32_e32 v31, 0xffff0000, v87
	v_pk_fma_f32 v[22:23], v[22:23], v[34:35], v[26:27]
	v_pk_fma_f32 v[20:21], v[20:21], v[32:33], v[24:25]
	v_lshlrev_b32_e32 v24, 16, v82
	v_and_b32_e32 v25, 0xffff0000, v82
	v_lshlrev_b32_e32 v26, 16, v83
	v_and_b32_e32 v27, 0xffff0000, v83
	v_pk_fma_f32 v[26:27], v[18:19], v[26:27], v[30:31]
	v_pk_fma_f32 v[18:19], v[16:17], v[24:25], v[28:29]
	v_cvt_pk_bf16_f32 v16, v20, v21
	v_cvt_pk_bf16_f32 v17, v22, v23
	v_cvt_pk_bf16_f32 v18, v18, v19
	v_cvt_pk_bf16_f32 v19, v26, v27
	global_store_dwordx4 v[98:99], v[16:19], off offset:256
	s_waitcnt vmcnt(9)
	v_lshlrev_b32_e32 v24, 16, v72
	v_and_b32_e32 v25, 0xffff0000, v72
	s_waitcnt vmcnt(8)
	v_lshlrev_b32_e32 v16, 16, v76
	v_and_b32_e32 v17, 0xffff0000, v76
	v_lshlrev_b32_e32 v18, 16, v77
	v_and_b32_e32 v19, 0xffff0000, v77
	v_lshlrev_b32_e32 v26, 16, v73
	v_and_b32_e32 v27, 0xffff0000, v73
	v_lshlrev_b32_e32 v20, 16, v78
	v_and_b32_e32 v21, 0xffff0000, v78
	v_lshlrev_b32_e32 v22, 16, v79
	v_and_b32_e32 v23, 0xffff0000, v79
	v_pk_fma_f32 v[14:15], v[14:15], v[26:27], v[18:19]
	v_pk_fma_f32 v[12:13], v[12:13], v[24:25], v[16:17]
	v_lshlrev_b32_e32 v16, 16, v74
	v_and_b32_e32 v17, 0xffff0000, v74
	v_lshlrev_b32_e32 v18, 16, v75
	v_and_b32_e32 v19, 0xffff0000, v75
	v_pk_fma_f32 v[18:19], v[10:11], v[18:19], v[22:23]
	v_pk_fma_f32 v[10:11], v[8:9], v[16:17], v[20:21]
	v_cvt_pk_bf16_f32 v8, v12, v13
	v_cvt_pk_bf16_f32 v9, v14, v15
	v_cvt_pk_bf16_f32 v10, v10, v11
	v_cvt_pk_bf16_f32 v11, v18, v19
	global_store_dwordx4 v[96:97], v[8:11], off
	s_waitcnt vmcnt(8)
	v_lshlrev_b32_e32 v16, 16, v64
	v_and_b32_e32 v17, 0xffff0000, v64
	s_waitcnt vmcnt(7)
	v_lshlrev_b32_e32 v8, 16, v68
	v_and_b32_e32 v9, 0xffff0000, v68
	v_lshlrev_b32_e32 v10, 16, v69
	v_and_b32_e32 v11, 0xffff0000, v69
	v_lshlrev_b32_e32 v18, 16, v65
	v_and_b32_e32 v19, 0xffff0000, v65
	v_lshlrev_b32_e32 v12, 16, v70
	v_and_b32_e32 v13, 0xffff0000, v70
	v_lshlrev_b32_e32 v14, 16, v71
	v_and_b32_e32 v15, 0xffff0000, v71
	v_pk_fma_f32 v[6:7], v[6:7], v[18:19], v[10:11]
	v_pk_fma_f32 v[4:5], v[4:5], v[16:17], v[8:9]
	v_lshlrev_b32_e32 v8, 16, v66
	v_and_b32_e32 v9, 0xffff0000, v66
	v_lshlrev_b32_e32 v10, 16, v67
	v_and_b32_e32 v11, 0xffff0000, v67
	v_pk_fma_f32 v[10:11], v[2:3], v[10:11], v[14:15]
	v_pk_fma_f32 v[2:3], v[0:1], v[8:9], v[12:13]
	v_cvt_pk_bf16_f32 v0, v4, v5
	v_cvt_pk_bf16_f32 v1, v6, v7
	v_cvt_pk_bf16_f32 v2, v2, v3
	v_cvt_pk_bf16_f32 v3, v10, v11
	global_store_dwordx4 v[96:97], v[0:3], off offset:256
	s_nop 1
	v_lshl_add_u64 v[0:1], v[92:93], 0, s[22:23]
	v_lshl_add_u64 v[2:3], v[94:95], 0, s[78:79]
	s_cbranch_vccnz .LBB0_709
	s_andn2_b64 vcc, exec, s[10:11]
	s_cbranch_vccnz .LBB0_708
	s_barrier
	s_branch .LBB0_708
